# m15: m10 + write-through (sc1) stores for weight-conversion fillers and prologue, L2 writeback skipped at seams whose only cross-XCD data are those (next-ph 1,2,8,10); final-norm rows remapped XCD-loc
# speedup vs baseline: 1.0205x; 1.0040x over previous
; __device__ __forceinline__ int tid_opaque() { int t = threadIdx.x; asm volatile("" : "+v"(t)); return t; }
; __device__ __forceinline__ void final_phase(const Args& a, int vcu, int G) {
;     const int tid = tid_opaque(), lane = tid & 63, wave = __builtin_amdgcn_readfirstlane(tid >> 6);
;     const int gw = vcu * 8 + wave, NGW = G * 8;
;     const float* ss = (const float*)(a.ws + WS_SS); const float* gn = a.in[18];
;     const f32x4* gr = (const f32x4*)gn + lane;
;     f32x4 gv[4];
; #pragma unroll
;     for (int j = 0; j < 4; ++j) gv[j] = gr[64 * j];
;     const bf16_t* xb = (const bf16_t*)(a.ws + WS_XB);
;     for (int row = gw; row < M; row += 4 * NGW) {
;         u32x2 v[4][4]; float r[4];
; #pragma unroll
;         for (int q = 0; q < 4; ++q) { const int rr = row + q * NGW < M ? row + q * NGW : row; const u32x2* xr = (const u32x2*)(xb + (size_t)rr * DM) + lane;
.LBB0_16:
	s_cmp_eq_u32 s76, 15
	s_mov_b64 s[42:43], -1
	s_cbranch_scc0 .LBB0_27
	v_mov_b32_e32 v0, v228
	v_readlane_b32 s1, v253, 5
	v_readfirstlane_b32 s0, v0
	s_ashr_i32 s0, s0, 6
	s_add_i32 s54, s0, s1
	s_cmpk_gt_i32 s54, 0x3fff
	s_cbranch_scc1 .LBB0_26
	s_lshr_b32 s0, s54, 8
	s_and_b32 s1, s54, 0xff
	s_lshl_b32 s0, s0, 11
	s_lshl_b32 s1, s1, 3
	s_add_i32 s54, s0, s1
	s_add_i32 s100, s54, 8
	s_mov_b32 s33, 1
	s_mov_b32 s4, 2
	s_mov_b32 s92, 3
	v_readlane_b32 s0, v254, 62
	v_readlane_b32 s1, v254, 63
	s_load_dwordx4 s[48:51], s[0:1], 0x90
	s_waitcnt vmcnt(7)
	v_and_b32_e32 v18, 63, v0
	v_lshlrev_b32_e32 v0, 4, v18
	v_lshlrev_b32_e32 v18, 3, v18
	v_mov_b32_e32 v19, v1
	s_waitcnt lgkmcnt(0)
	global_load_dwordx4 v[2:5], v0, s[48:49]
	global_load_dwordx4 v[6:9], v0, s[48:49] offset:1024
	global_load_dwordx4 v[10:13], v0, s[48:49] offset:2048
	global_load_dwordx4 v[14:17], v0, s[48:49] offset:3072
	v_lshl_add_u64 v[66:67], s[74:75], 0, v[18:19]
	v_lshl_add_u64 v[68:69], s[50:51], 0, v[0:1]
	s_branch .LBB0_20
.LBB0_19:
	s_add_i32 s0, s42, s33
	s_add_i32 s0, s0, s33
	s_add_i32 s54, s0, s33
	s_cmp_ge_i32 s54, s100
	s_cbranch_scc1 .LBB0_26

; #define LAS __attribute__((address_space(3)))
; __device__ __forceinline__ unsigned cvtpk(float lo, float hi) { f32x2_t v = {lo, hi}; bf16x2_t b = __builtin_convertvector(v, bf16x2_t); return __builtin_bit_cast(unsigned, b); }
; __device__ __forceinline__ void transpose_item(const float* __restrict__ W, int K, int N, const float* __restrict__ gain, bf16_t* __restrict__ WT, int mode, LAS float* scr, int item, int lane) {
;     ...
;     const int rb = mode == 0 ? n0 : ((n0 >> 7) * 256 + (n0 & 127) + (mode == 2 ? 128 : 0));
;     const int c = lane & 7;
;     f32x4 g0 = {1.f, 1.f, 1.f, 1.f}, g1 = g0;
;     if (gain) { g0 = *(const f32x4*)(gain + k0 + 8 * c); g1 = *(const f32x4*)(gain + k0 + 8 * c + 4); }
; #pragma unroll
;     for (int j = 0; j < 4; ++j) { const int n = (lane >> 3) + 8 * j; const LAS float* s = scr + (8 * c) * 33 + n;
;         u32x4 o; o.x = cvtpk(s[0 * 33] * g0[0], s[1 * 33] * g0[1]); o.y = cvtpk(s[2 * 33] * g0[2], s[3 * 33] * g0[3]); o.z = cvtpk(s[4 * 33] * g1[0], s[5 * 33] * g1[1]); o.w = cvtpk(s[6 * 33] * g1[2], s[7 * 33] * g1[3]);
;         *(u32x4*)(WT + (size_t)(rb + n) * K + k0 + 8 * c) = o; }
.LBB0_59:
	s_and_b32 s2, s54, 0x60
	ds_read2_b32 v[24:25], v15 offset1:8
	ds_read2_b32 v[26:27], v15 offset0:33 offset1:41
	ds_read2_b32 v[30:31], v15 offset0:66 offset1:74
	ds_read2_b32 v[32:33], v15 offset0:99 offset1:107
	s_or_b32 s2, s2, s4
	s_lshl_b32 s4, s48, 6
	s_and_b32 s4, s4, 0xffffff00
	ds_read2_b32 v[34:35], v15 offset0:132 offset1:140
	ds_read2_b32 v[36:37], v15 offset0:165 offset1:173
	ds_read2_b32 v[38:39], v15 offset0:198 offset1:206
	ds_read2_b32 v[40:41], v15 offset0:231 offset1:239
	s_or_b32 s2, s2, s4
	s_and_b64 s[44:45], s[44:45], exec
	s_cselect_b32 s2, s54, s2
	s_lshl_b64 s[44:45], s[52:53], 1
	s_waitcnt lgkmcnt(7)
	v_mov_b32_e32 v20, v24
	s_waitcnt lgkmcnt(6)
	v_mov_b32_e32 v21, v26
	s_waitcnt lgkmcnt(5)
	v_mov_b32_e32 v22, v30
	s_waitcnt lgkmcnt(4)
	v_mov_b32_e32 v23, v32
	s_add_u32 s42, s42, s44
	s_waitcnt vmcnt(1)
	v_pk_mul_f32 v[20:21], v[2:3], v[20:21]
	v_pk_mul_f32 v[22:23], v[4:5], v[22:23]
	s_addc_u32 s43, s43, s45
	v_mov_b32_e32 v13, v1
	v_cvt_pk_bf16_f32 v20, v20, v21
	v_cvt_pk_bf16_f32 v21, v22, v23
	s_waitcnt lgkmcnt(3)
	v_mov_b32_e32 v22, v34
	s_waitcnt lgkmcnt(2)
	v_mov_b32_e32 v23, v36
	s_waitcnt lgkmcnt(1)
	v_mov_b32_e32 v42, v38
	s_waitcnt lgkmcnt(0)
	v_mov_b32_e32 v43, v40
	v_lshl_add_u64 v[28:29], s[42:43], 0, v[12:13]
	s_waitcnt vmcnt(0)
	v_pk_mul_f32 v[22:23], v[6:7], v[22:23]
	v_pk_mul_f32 v[42:43], v[8:9], v[42:43]
	v_or_b32_e32 v13, s2, v14
	s_ashr_i32 s4, s2, 31
	v_cvt_pk_bf16_f32 v22, v22, v23
	v_cvt_pk_bf16_f32 v23, v42, v43
	v_mul_lo_u32 v24, s41, v13
	v_mad_u64_u32 v[42:43], s[42:43], s40, v13, 0
	s_mul_i32 s4, s40, s4
	v_add3_u32 v43, v43, s4, v24
	v_lshl_add_u64 v[42:43], v[42:43], 1, v[28:29]
	v_mov_b32_e32 v26, v25
	v_mov_b32_e32 v32, v31
	global_store_dwordx4 v[42:43], v[20:23], off sc1
	v_mov_b32_e32 v36, v35
	v_mov_b32_e32 v40, v39
	v_pk_mul_f32 v[20:21], v[2:3], v[26:27]
	v_pk_mul_f32 v[22:23], v[4:5], v[32:33]
	v_cvt_pk_bf16_f32 v20, v20, v21
	v_cvt_pk_bf16_f32 v21, v22, v23
	v_pk_mul_f32 v[22:23], v[6:7], v[36:37]
	v_pk_mul_f32 v[24:25], v[8:9], v[40:41]
	v_or_b32_e32 v13, s2, v16
	v_cvt_pk_bf16_f32 v22, v22, v23
	v_cvt_pk_bf16_f32 v23, v24, v25
	v_mul_lo_u32 v30, s41, v13
	v_mad_u64_u32 v[24:25], s[42:43], s40, v13, 0
	v_add3_u32 v25, v25, s4, v30
	v_lshl_add_u64 v[24:25], v[24:25], 1, v[28:29]
	ds_read2_b32 v[26:27], v15 offset0:16 offset1:24
	ds_read2_b32 v[30:31], v15 offset0:49 offset1:57
	global_store_dwordx4 v[24:25], v[20:23], off sc1
	ds_read2_b32 v[24:25], v15 offset0:82 offset1:90
	ds_read2_b32 v[32:33], v15 offset0:115 offset1:123
	ds_read2_b32 v[34:35], v15 offset0:148 offset1:156
	ds_read2_b32 v[36:37], v15 offset0:181 offset1:189
	ds_read2_b32 v[38:39], v15 offset0:214 offset1:222
	ds_read2_b32 v[40:41], v15 offset0:247 offset1:255
	s_waitcnt lgkmcnt(7)
	v_mov_b32_e32 v20, v26
	s_waitcnt lgkmcnt(6)
	v_mov_b32_e32 v21, v30
	s_waitcnt lgkmcnt(5)
	v_mov_b32_e32 v22, v24
	s_waitcnt lgkmcnt(4)
	v_mov_b32_e32 v23, v32
	v_pk_mul_f32 v[20:21], v[2:3], v[20:21]
	v_pk_mul_f32 v[22:23], v[4:5], v[22:23]
	v_mov_b32_e32 v30, v27
	v_mov_b32_e32 v32, v25
	v_cvt_pk_bf16_f32 v20, v20, v21
	v_cvt_pk_bf16_f32 v21, v22, v23
	s_waitcnt lgkmcnt(3)
	v_mov_b32_e32 v22, v34
	s_waitcnt lgkmcnt(2)
	v_mov_b32_e32 v23, v36
	s_waitcnt lgkmcnt(0)
	v_mov_b32_e32 v43, v40
	v_pk_mul_f32 v[2:3], v[2:3], v[30:31]
	v_pk_mul_f32 v[4:5], v[4:5], v[32:33]
	v_mov_b32_e32 v36, v35
	v_mov_b32_e32 v40, v39
	v_pk_mul_f32 v[22:23], v[6:7], v[22:23]
	v_mov_b32_e32 v42, v38
	v_cvt_pk_bf16_f32 v2, v2, v3
	v_cvt_pk_bf16_f32 v3, v4, v5
	v_pk_mul_f32 v[4:5], v[6:7], v[36:37]
	v_pk_mul_f32 v[6:7], v[8:9], v[40:41]
	v_pk_mul_f32 v[42:43], v[8:9], v[42:43]
	v_or_b32_e32 v13, s2, v17
	v_cvt_pk_bf16_f32 v4, v4, v5
	v_cvt_pk_bf16_f32 v5, v6, v7
	v_or_b32_e32 v6, s2, v18
	v_cvt_pk_bf16_f32 v22, v22, v23
	v_cvt_pk_bf16_f32 v23, v42, v43
	v_mul_lo_u32 v24, s41, v13
	v_mad_u64_u32 v[42:43], s[42:43], s40, v13, 0
	v_mul_lo_u32 v8, s41, v6
	v_mad_u64_u32 v[6:7], s[40:41], s40, v6, 0
	v_add3_u32 v43, v43, s4, v24
	v_add3_u32 v7, v7, s4, v8
	v_lshl_add_u64 v[42:43], v[42:43], 1, v[28:29]
	v_lshl_add_u64 v[6:7], v[6:7], 1, v[28:29]
	global_store_dwordx4 v[42:43], v[20:23], off sc1
	global_store_dwordx4 v[6:7], v[2:5], off sc1
	v_readlane_b32 s2, v254, 33
	s_waitcnt lgkmcnt(0)
	s_add_i32 s1, s1, s2
	s_cmp_ge_i32 s1, s0
	s_cbranch_scc1 .LBB0_89

; #define LAS __attribute__((address_space(3)))
; __device__ __forceinline__ unsigned cvtpk(float lo, float hi) { f32x2_t v = {lo, hi}; bf16x2_t b = __builtin_convertvector(v, bf16x2_t); return __builtin_bit_cast(unsigned, b); }
; __device__ __forceinline__ void transpose_item(const float* __restrict__ W, int K, int N, const float* __restrict__ gain, bf16_t* __restrict__ WT, int mode, LAS float* scr, int item, int lane) {
;     ...
;     const int rb = mode == 0 ? n0 : ((n0 >> 7) * 256 + (n0 & 127) + (mode == 2 ? 128 : 0));
;     const int c = lane & 7;
;     f32x4 g0 = {1.f, 1.f, 1.f, 1.f}, g1 = g0;
;     if (gain) { g0 = *(const f32x4*)(gain + k0 + 8 * c); g1 = *(const f32x4*)(gain + k0 + 8 * c + 4); }
; #pragma unroll
;     for (int j = 0; j < 4; ++j) { const int n = (lane >> 3) + 8 * j; const LAS float* s = scr + (8 * c) * 33 + n;
;         u32x4 o; o.x = cvtpk(s[0 * 33] * g0[0], s[1 * 33] * g0[1]); o.y = cvtpk(s[2 * 33] * g0[2], s[3 * 33] * g0[3]); o.z = cvtpk(s[4 * 33] * g1[0], s[5 * 33] * g1[1]); o.w = cvtpk(s[6 * 33] * g1[2], s[7 * 33] * g1[3]);
;         *(u32x4*)(WT + (size_t)(rb + n) * K + k0 + 8 * c) = o; }
.LBB0_288:
	s_and_b32 s9, s52, 0x60
	ds_read2_b32 v[24:25], v15 offset1:8
	ds_read2_b32 v[26:27], v15 offset0:33 offset1:41
	ds_read2_b32 v[30:31], v15 offset0:66 offset1:74
	ds_read2_b32 v[32:33], v15 offset0:99 offset1:107
	s_or_b32 s4, s9, s4
	s_lshl_b32 s9, s58, 6
	s_and_b32 s9, s9, 0xffffff00
	ds_read2_b32 v[34:35], v15 offset0:132 offset1:140
	ds_read2_b32 v[36:37], v15 offset0:165 offset1:173
	ds_read2_b32 v[38:39], v15 offset0:198 offset1:206
	ds_read2_b32 v[40:41], v15 offset0:231 offset1:239
	s_or_b32 s4, s4, s9
	s_and_b64 s[44:45], s[44:45], exec
	s_cselect_b32 s4, s52, s4
	s_lshl_b64 s[44:45], s[50:51], 1
	s_waitcnt lgkmcnt(7)
	v_mov_b32_e32 v20, v24
	s_waitcnt lgkmcnt(6)
	v_mov_b32_e32 v21, v26
	s_waitcnt lgkmcnt(5)
	v_mov_b32_e32 v22, v30
	s_waitcnt lgkmcnt(4)
	v_mov_b32_e32 v23, v32
	s_add_u32 s42, s42, s44
	s_waitcnt vmcnt(1)
	v_pk_mul_f32 v[20:21], v[2:3], v[20:21]
	v_pk_mul_f32 v[22:23], v[4:5], v[22:23]
	s_addc_u32 s43, s43, s45
	v_mov_b32_e32 v13, v1
	v_cvt_pk_bf16_f32 v20, v20, v21
	v_cvt_pk_bf16_f32 v21, v22, v23
	s_waitcnt lgkmcnt(3)
	v_mov_b32_e32 v22, v34
	s_waitcnt lgkmcnt(2)
	v_mov_b32_e32 v23, v36
	s_waitcnt lgkmcnt(1)
	v_mov_b32_e32 v42, v38
	s_waitcnt lgkmcnt(0)
	v_mov_b32_e32 v43, v40
	v_lshl_add_u64 v[28:29], s[42:43], 0, v[12:13]
	s_waitcnt vmcnt(0)
	v_pk_mul_f32 v[22:23], v[6:7], v[22:23]
	v_pk_mul_f32 v[42:43], v[8:9], v[42:43]
	v_or_b32_e32 v13, s4, v14
	s_ashr_i32 s9, s4, 31
	v_cvt_pk_bf16_f32 v22, v22, v23
	v_cvt_pk_bf16_f32 v23, v42, v43
	v_mul_lo_u32 v24, s41, v13
	v_mad_u64_u32 v[42:43], s[42:43], s40, v13, 0
	s_mul_i32 s9, s40, s9
	v_add3_u32 v43, v43, s9, v24
	v_lshl_add_u64 v[42:43], v[42:43], 1, v[28:29]
	v_mov_b32_e32 v26, v25
	v_mov_b32_e32 v32, v31
	global_store_dwordx4 v[42:43], v[20:23], off sc1
	v_mov_b32_e32 v36, v35
	v_mov_b32_e32 v40, v39
	v_pk_mul_f32 v[20:21], v[2:3], v[26:27]
	v_pk_mul_f32 v[22:23], v[4:5], v[32:33]
	v_cvt_pk_bf16_f32 v20, v20, v21
	v_cvt_pk_bf16_f32 v21, v22, v23
	v_pk_mul_f32 v[22:23], v[6:7], v[36:37]
	v_pk_mul_f32 v[24:25], v[8:9], v[40:41]
	v_or_b32_e32 v13, s4, v16
	v_cvt_pk_bf16_f32 v22, v22, v23
	v_cvt_pk_bf16_f32 v23, v24, v25
	v_mul_lo_u32 v30, s41, v13
	v_mad_u64_u32 v[24:25], s[42:43], s40, v13, 0
	v_add3_u32 v25, v25, s9, v30
	v_lshl_add_u64 v[24:25], v[24:25], 1, v[28:29]
	ds_read2_b32 v[26:27], v15 offset0:16 offset1:24
	ds_read2_b32 v[30:31], v15 offset0:49 offset1:57
	global_store_dwordx4 v[24:25], v[20:23], off sc1
	ds_read2_b32 v[24:25], v15 offset0:82 offset1:90
	ds_read2_b32 v[32:33], v15 offset0:115 offset1:123
	ds_read2_b32 v[34:35], v15 offset0:148 offset1:156
	ds_read2_b32 v[36:37], v15 offset0:181 offset1:189
	ds_read2_b32 v[38:39], v15 offset0:214 offset1:222
	ds_read2_b32 v[40:41], v15 offset0:247 offset1:255
	s_waitcnt lgkmcnt(7)
	v_mov_b32_e32 v20, v26
	s_waitcnt lgkmcnt(6)
	v_mov_b32_e32 v21, v30
	s_waitcnt lgkmcnt(5)
	v_mov_b32_e32 v22, v24
	s_waitcnt lgkmcnt(4)
	v_mov_b32_e32 v23, v32
	v_pk_mul_f32 v[20:21], v[2:3], v[20:21]
	v_pk_mul_f32 v[22:23], v[4:5], v[22:23]
	v_mov_b32_e32 v30, v27
	v_mov_b32_e32 v32, v25
	v_cvt_pk_bf16_f32 v20, v20, v21
	v_cvt_pk_bf16_f32 v21, v22, v23
	s_waitcnt lgkmcnt(3)
	v_mov_b32_e32 v22, v34
	s_waitcnt lgkmcnt(2)
	v_mov_b32_e32 v23, v36
	s_waitcnt lgkmcnt(0)
	v_mov_b32_e32 v43, v40
	v_pk_mul_f32 v[2:3], v[2:3], v[30:31]
	v_pk_mul_f32 v[4:5], v[4:5], v[32:33]
	v_mov_b32_e32 v36, v35
	v_mov_b32_e32 v40, v39
	v_pk_mul_f32 v[22:23], v[6:7], v[22:23]
	v_mov_b32_e32 v42, v38
	v_cvt_pk_bf16_f32 v2, v2, v3
	v_cvt_pk_bf16_f32 v3, v4, v5
	v_pk_mul_f32 v[4:5], v[6:7], v[36:37]
	v_pk_mul_f32 v[6:7], v[8:9], v[40:41]
	v_pk_mul_f32 v[42:43], v[8:9], v[42:43]
	v_or_b32_e32 v13, s4, v17
	v_cvt_pk_bf16_f32 v4, v4, v5
	v_cvt_pk_bf16_f32 v5, v6, v7
	v_or_b32_e32 v6, s4, v18
	v_cvt_pk_bf16_f32 v22, v22, v23
	v_cvt_pk_bf16_f32 v23, v42, v43
	v_mul_lo_u32 v24, s41, v13
	v_mad_u64_u32 v[42:43], s[42:43], s40, v13, 0
	v_mul_lo_u32 v8, s41, v6
	v_mad_u64_u32 v[6:7], s[40:41], s40, v6, 0
	v_add3_u32 v43, v43, s9, v24
	v_add3_u32 v7, v7, s9, v8
	v_lshl_add_u64 v[42:43], v[42:43], 1, v[28:29]
	v_lshl_add_u64 v[6:7], v[6:7], 1, v[28:29]
	global_store_dwordx4 v[42:43], v[20:23], off sc1
	global_store_dwordx4 v[6:7], v[2:5], off sc1
	v_readlane_b32 s2, v254, 37
	s_waitcnt lgkmcnt(0)
	s_add_i32 s1, s1, s2
	s_cmp_ge_i32 s1, s0
	s_cbranch_scc1 .LBB0_318

; #define LAS __attribute__((address_space(3)))
; __device__ __forceinline__ unsigned cvtpk(float lo, float hi) { f32x2_t v = {lo, hi}; bf16x2_t b = __builtin_convertvector(v, bf16x2_t); return __builtin_bit_cast(unsigned, b); }
; __device__ __forceinline__ void transpose_item(const float* __restrict__ W, int K, int N, const float* __restrict__ gain, bf16_t* __restrict__ WT, int mode, LAS float* scr, int item, int lane) {
;     ...
;     const int rb = mode == 0 ? n0 : ((n0 >> 7) * 256 + (n0 & 127) + (mode == 2 ? 128 : 0));
;     const int c = lane & 7;
;     f32x4 g0 = {1.f, 1.f, 1.f, 1.f}, g1 = g0;
;     if (gain) { g0 = *(const f32x4*)(gain + k0 + 8 * c); g1 = *(const f32x4*)(gain + k0 + 8 * c + 4); }
; #pragma unroll
;     for (int j = 0; j < 4; ++j) { const int n = (lane >> 3) + 8 * j; const LAS float* s = scr + (8 * c) * 33 + n;
;         u32x4 o; o.x = cvtpk(s[0 * 33] * g0[0], s[1 * 33] * g0[1]); o.y = cvtpk(s[2 * 33] * g0[2], s[3 * 33] * g0[3]); o.z = cvtpk(s[4 * 33] * g1[0], s[5 * 33] * g1[1]); o.w = cvtpk(s[6 * 33] * g1[2], s[7 * 33] * g1[3]);
;         *(u32x4*)(WT + (size_t)(rb + n) * K + k0 + 8 * c) = o; }
.LBB0_322:
	ds_read2_b32 v[26:27], v16 offset1:8
	ds_read2_b32 v[28:29], v16 offset0:33 offset1:41
	ds_read2_b32 v[32:33], v16 offset0:66 offset1:74
	ds_read2_b32 v[34:35], v16 offset0:99 offset1:107
	s_mul_hi_i32 s9, s1, 0x2780000
	s_mul_i32 s1, s1, 0x2780000
	v_readlane_b32 s58, v252, 0
	ds_read2_b32 v[36:37], v16 offset0:132 offset1:140
	ds_read2_b32 v[38:39], v16 offset0:165 offset1:173
	ds_read2_b32 v[40:41], v16 offset0:198 offset1:206
	ds_read2_b32 v[42:43], v16 offset0:231 offset1:239
	v_readlane_b32 s59, v252, 1
	s_add_u32 s1, s58, s1
	s_addc_u32 s9, s59, s9
	s_and_b64 s[52:53], s[52:53], exec
	s_waitcnt lgkmcnt(7)
	v_mov_b32_e32 v22, v26
	s_waitcnt lgkmcnt(6)
	v_mov_b32_e32 v23, v28
	s_waitcnt lgkmcnt(5)
	v_mov_b32_e32 v24, v32
	s_waitcnt lgkmcnt(4)
	v_mov_b32_e32 v25, v34
	s_cselect_b32 s18, 0, 0x80
	s_and_b32 s45, s80, 0x60
	s_lshl_b32 s4, s4, 6
	s_waitcnt vmcnt(1)
	v_pk_mul_f32 v[22:23], v[2:3], v[22:23]
	v_pk_mul_f32 v[24:25], v[4:5], v[24:25]
	s_or_b32 s18, s45, s18
	s_and_b32 s4, s4, 0xffffff00
	v_cvt_pk_bf16_f32 v22, v22, v23
	v_cvt_pk_bf16_f32 v23, v24, v25
	s_waitcnt lgkmcnt(3)
	v_mov_b32_e32 v24, v36
	s_waitcnt lgkmcnt(2)
	v_mov_b32_e32 v25, v38
	s_waitcnt lgkmcnt(1)
	v_mov_b32_e32 v44, v40
	s_waitcnt lgkmcnt(0)
	v_mov_b32_e32 v45, v42
	s_or_b32 s4, s18, s4
	s_lshl_b64 s[52:53], s[54:55], 1
	s_waitcnt vmcnt(0)
	v_pk_mul_f32 v[24:25], v[6:7], v[24:25]
	v_pk_mul_f32 v[44:45], v[8:9], v[44:45]
	s_add_u32 s52, s1, s52
	v_cvt_pk_bf16_f32 v24, v24, v25
	v_cvt_pk_bf16_f32 v25, v44, v45
	v_or_b32_e32 v44, s4, v15
	s_addc_u32 s53, s9, s53
	v_mov_b32_e32 v13, v1
	v_ashrrev_i32_e32 v45, 31, v44
	v_lshl_add_u64 v[30:31], s[52:53], 0, v[12:13]
	v_lshlrev_b64 v[44:45], 11, v[44:45]
	v_lshl_add_u64 v[44:45], v[30:31], 0, v[44:45]
	v_mov_b32_e32 v28, v27
	v_mov_b32_e32 v34, v33
	global_store_dwordx4 v[44:45], v[22:25], off sc1
	v_mov_b32_e32 v38, v37
	v_mov_b32_e32 v42, v41
	v_pk_mul_f32 v[22:23], v[2:3], v[28:29]
	v_pk_mul_f32 v[24:25], v[4:5], v[34:35]
	v_cvt_pk_bf16_f32 v22, v22, v23
	v_cvt_pk_bf16_f32 v23, v24, v25
	v_pk_mul_f32 v[24:25], v[6:7], v[38:39]
	v_pk_mul_f32 v[26:27], v[8:9], v[42:43]
	v_cvt_pk_bf16_f32 v24, v24, v25
	v_cvt_pk_bf16_f32 v25, v26, v27
	v_or_b32_e32 v26, s4, v17
	v_ashrrev_i32_e32 v27, 31, v26
	v_lshlrev_b64 v[26:27], 11, v[26:27]
	v_lshl_add_u64 v[26:27], v[30:31], 0, v[26:27]
	ds_read2_b32 v[28:29], v16 offset0:16 offset1:24
	ds_read2_b32 v[32:33], v16 offset0:49 offset1:57
	global_store_dwordx4 v[26:27], v[22:25], off sc1
	ds_read2_b32 v[26:27], v16 offset0:82 offset1:90
	ds_read2_b32 v[34:35], v16 offset0:115 offset1:123
	ds_read2_b32 v[36:37], v16 offset0:148 offset1:156
	ds_read2_b32 v[38:39], v16 offset0:181 offset1:189
	ds_read2_b32 v[40:41], v16 offset0:214 offset1:222
	ds_read2_b32 v[42:43], v16 offset0:247 offset1:255
	s_waitcnt lgkmcnt(7)
	v_mov_b32_e32 v22, v28
	s_waitcnt lgkmcnt(6)
	v_mov_b32_e32 v23, v32
	s_waitcnt lgkmcnt(5)
	v_mov_b32_e32 v24, v26
	s_waitcnt lgkmcnt(4)
	v_mov_b32_e32 v25, v34
	v_pk_mul_f32 v[22:23], v[2:3], v[22:23]
	v_pk_mul_f32 v[24:25], v[4:5], v[24:25]
	v_mov_b32_e32 v32, v29
	v_mov_b32_e32 v34, v27
	v_cvt_pk_bf16_f32 v22, v22, v23
	v_cvt_pk_bf16_f32 v23, v24, v25
	s_waitcnt lgkmcnt(3)
	v_mov_b32_e32 v24, v36
	s_waitcnt lgkmcnt(2)
	v_mov_b32_e32 v25, v38
	s_waitcnt lgkmcnt(1)
	v_mov_b32_e32 v44, v40
	s_waitcnt lgkmcnt(0)
	v_mov_b32_e32 v45, v42
	v_pk_mul_f32 v[2:3], v[2:3], v[32:33]
	v_pk_mul_f32 v[4:5], v[4:5], v[34:35]
	v_mov_b32_e32 v38, v37
	v_mov_b32_e32 v42, v41
	v_pk_mul_f32 v[24:25], v[6:7], v[24:25]
	v_pk_mul_f32 v[44:45], v[8:9], v[44:45]
	v_cvt_pk_bf16_f32 v2, v2, v3
	v_cvt_pk_bf16_f32 v3, v4, v5
	v_pk_mul_f32 v[4:5], v[6:7], v[38:39]
	v_pk_mul_f32 v[6:7], v[8:9], v[42:43]
	v_cvt_pk_bf16_f32 v24, v24, v25
	v_cvt_pk_bf16_f32 v25, v44, v45
	v_or_b32_e32 v44, s4, v18
	v_cvt_pk_bf16_f32 v4, v4, v5
	v_cvt_pk_bf16_f32 v5, v6, v7
	v_or_b32_e32 v6, s4, v19
	v_ashrrev_i32_e32 v45, 31, v44
	v_ashrrev_i32_e32 v7, 31, v6
	v_lshlrev_b64 v[44:45], 11, v[44:45]
	v_lshlrev_b64 v[6:7], 11, v[6:7]
	v_lshl_add_u64 v[44:45], v[30:31], 0, v[44:45]
	v_lshl_add_u64 v[6:7], v[30:31], 0, v[6:7]
	global_store_dwordx4 v[44:45], v[22:25], off sc1
	global_store_dwordx4 v[6:7], v[2:5], off sc1
	s_waitcnt lgkmcnt(0)
	s_add_i32 s0, s0, s33
	s_cmpk_lt_i32 s0, 0xb00
	s_cbranch_scc0 .LBB0_325

; __device__ __forceinline__ unsigned cvtpk(float lo, float hi) { f32x2_t v = {lo, hi}; bf16x2_t b = __builtin_convertvector(v, bf16x2_t); return __builtin_bit_cast(unsigned, b); }
; __device__ __forceinline__ void prologue_phase(LAS unsigned char* lds, const Args& a, int vcu, int G) {
;     ...
;     const float* x = a.in[0]; bf16_t* xb = (bf16_t*)(a.ws + WS_XB); float* ss = (float*)(a.ws + WS_SS);
;     for (int row = gw; row < M; row += 4 * NGW) {
;         f32x4 v[4][4];
; #pragma unroll
;         for (int q = 0; q < 4; ++q) { const int rr = row + q * NGW < M ? row + q * NGW : row; const f32x4* xr = (const f32x4*)(x + (size_t)rr * DM) + lane;
; #pragma unroll
;             for (int j = 0; j < 4; ++j) v[q][j] = __builtin_nontemporal_load(xr + 64 * j); }
; #pragma unroll
;         for (int q = 0; q < 4; ++q) { const int rr = row + q * NGW; if (rr < M) { u32x2* o = (u32x2*)(xb + (size_t)rr * DM) + lane; float s = 0.f;
; #pragma unroll
;             for (int j = 0; j < 4; ++j) { const f32x4 t = v[q][j]; s += (t[0] * t[0] + t[1] * t[1]) + (t[2] * t[2] + t[3] * t[3]); o[64 * j] = (u32x2){cvtpk(t[0], t[1]), cvtpk(t[2], t[3])}; }
;             s = wave_sum(s);
;             if (lane < 16) ss[(size_t)rr * 16 + lane] = lane == 0 ? s : 0.f; } }
.LBB0_329:
	s_ashr_i32 s45, s44, 31
	s_add_i32 s48, s44, s33
	s_cmpk_lt_i32 s48, 0x4000
	s_cselect_b64 s[74:75], -1, 0
	s_and_b64 s[0:1], s[74:75], exec
	s_cselect_b32 s0, s48, s44
	s_ashr_i32 s1, s0, 31
	s_lshl_b64 s[0:1], s[0:1], 12
	s_add_i32 s52, s4, s44
	s_cmpk_lt_i32 s52, 0x4000
	s_cselect_b64 s[72:73], -1, 0
	s_and_b64 s[50:51], s[72:73], exec
	s_cselect_b32 s50, s52, s44
	s_ashr_i32 s51, s50, 31
	s_lshl_b64 s[58:59], s[50:51], 12
	s_add_i32 s50, s92, s44
	s_cmpk_lt_i32 s50, 0x4000
	s_cselect_b64 s[54:55], -1, 0
	s_and_b64 s[60:61], s[54:55], exec
	s_cselect_b32 s60, s50, s44
	s_lshl_b64 s[70:71], s[44:45], 12
	s_waitcnt vmcnt(4)
	v_lshl_add_u64 v[2:3], v[50:51], 0, s[70:71]
	s_waitcnt lgkmcnt(0)
	global_load_dwordx4 v[62:65], v[2:3], off nt
	global_load_dwordx4 v[66:69], v[2:3], off offset:1024 nt
	global_load_dwordx4 v[70:73], v[2:3], off offset:2048 nt
	global_load_dwordx4 v[74:77], v[2:3], off offset:3072 nt
	v_lshl_add_u64 v[2:3], v[50:51], 0, s[0:1]
	s_ashr_i32 s61, s60, 31
	global_load_dwordx4 v[46:49], v[2:3], off nt
	global_load_dwordx4 v[42:45], v[2:3], off offset:1024 nt
	global_load_dwordx4 v[38:41], v[2:3], off offset:2048 nt
	global_load_dwordx4 v[34:37], v[2:3], off offset:3072 nt
	v_lshl_add_u64 v[2:3], v[50:51], 0, s[58:59]
	s_lshl_b64 s[0:1], s[60:61], 12
	global_load_dwordx4 v[30:33], v[2:3], off nt
	global_load_dwordx4 v[26:29], v[2:3], off offset:1024 nt
	global_load_dwordx4 v[22:25], v[2:3], off offset:2048 nt
	global_load_dwordx4 v[18:21], v[2:3], off offset:3072 nt
	v_lshl_add_u64 v[2:3], v[50:51], 0, s[0:1]
	global_load_dwordx4 v[14:17], v[2:3], off nt
	global_load_dwordx4 v[10:13], v[2:3], off offset:1024 nt
	global_load_dwordx4 v[6:9], v[2:3], off offset:2048 nt
	s_nop 0
	global_load_dwordx4 v[2:5], v[2:3], off offset:3072 nt
	s_lshl_b64 s[0:1], s[44:45], 11
	s_waitcnt vmcnt(15)
	v_mul_f32_e32 v61, v63, v63
	v_mul_f32_e32 v78, v65, v65
	s_waitcnt vmcnt(14)
	v_mul_f32_e32 v79, v67, v67
	v_mul_f32_e32 v80, v69, v69
	s_waitcnt vmcnt(13)
	v_mul_f32_e32 v81, v71, v71
	v_mul_f32_e32 v82, v73, v73
	v_fmac_f32_e32 v61, v62, v62
	v_fmac_f32_e32 v78, v64, v64
	v_fmac_f32_e32 v79, v66, v66
	v_fmac_f32_e32 v80, v68, v68
	s_waitcnt vmcnt(12)
	v_mul_f32_e32 v83, v75, v75
	v_mul_f32_e32 v84, v77, v77
	v_fmac_f32_e32 v81, v70, v70
	v_fmac_f32_e32 v82, v72, v72
	v_add_f32_e32 v61, v61, v78
	v_add_f32_e32 v78, v79, v80
	v_fmac_f32_e32 v83, v74, v74
	v_fmac_f32_e32 v84, v76, v76
	v_add_f32_e32 v79, v81, v82
	v_add_f32_e32 v61, v78, v61
	v_add_f32_e32 v61, v79, v61
	v_add_f32_e32 v78, v83, v84
	v_add_f32_e32 v61, v78, v61
	ds_bpermute_b32 v78, v0, v61
	v_cvt_pk_bf16_f32 v62, v62, v63
	v_cvt_pk_bf16_f32 v63, v64, v65
	v_cvt_pk_bf16_f32 v64, v70, v71
	v_cvt_pk_bf16_f32 v65, v72, v73
	s_waitcnt lgkmcnt(0)
	v_add_f32_e32 v61, v61, v78
	ds_bpermute_b32 v78, v56, v61
	s_waitcnt lgkmcnt(0)
	v_add_f32_e32 v61, v61, v78
	ds_bpermute_b32 v80, v57, v61
	v_lshl_add_u64 v[78:79], v[52:53], 0, s[0:1]
	global_store_dwordx2 v[78:79], v[62:63], off sc1
	v_cvt_pk_bf16_f32 v62, v66, v67
	v_cvt_pk_bf16_f32 v63, v68, v69
	s_waitcnt lgkmcnt(0)
	v_add_f32_e32 v61, v61, v80
	ds_bpermute_b32 v80, v58, v61
	global_store_dwordx2 v[78:79], v[62:63], off offset:512 sc1
	global_store_dwordx2 v[78:79], v[64:65], off offset:1024 sc1
	v_cvt_pk_bf16_f32 v64, v74, v75
	v_cvt_pk_bf16_f32 v65, v76, v77
	s_waitcnt lgkmcnt(0)
	v_add_f32_e32 v61, v61, v80
	ds_bpermute_b32 v66, v59, v61
	global_store_dwordx2 v[78:79], v[64:65], off offset:1536 sc1
	s_waitcnt lgkmcnt(0)
	v_add_f32_e32 v61, v61, v66
	ds_bpermute_b32 v62, v60, v61
	s_and_saveexec_b64 s[76:77], s[40:41]
	s_cbranch_execnz .LBB0_333
	s_or_b64 exec, exec, s[76:77]
	s_andn2_b64 vcc, exec, s[74:75]
	s_cbranch_vccz .LBB0_334

; __device__ __forceinline__ unsigned cvtpk(float lo, float hi) { f32x2_t v = {lo, hi}; bf16x2_t b = __builtin_convertvector(v, bf16x2_t); return __builtin_bit_cast(unsigned, b); }
; __device__ __forceinline__ void prologue_phase(LAS unsigned char* lds, const Args& a, int vcu, int G) {
;     ...
;     const float* x = a.in[0]; bf16_t* xb = (bf16_t*)(a.ws + WS_XB); float* ss = (float*)(a.ws + WS_SS);
;     for (int row = gw; row < M; row += 4 * NGW) {
;         f32x4 v[4][4];
; #pragma unroll
;         for (int q = 0; q < 4; ++q) { const int rr = row + q * NGW < M ? row + q * NGW : row; const f32x4* xr = (const f32x4*)(x + (size_t)rr * DM) + lane;
; #pragma unroll
;             for (int j = 0; j < 4; ++j) v[q][j] = __builtin_nontemporal_load(xr + 64 * j); }
; #pragma unroll
;         for (int q = 0; q < 4; ++q) { const int rr = row + q * NGW; if (rr < M) { u32x2* o = (u32x2*)(xb + (size_t)rr * DM) + lane; float s = 0.f;
; #pragma unroll
;             for (int j = 0; j < 4; ++j) { const f32x4 t = v[q][j]; s += (t[0] * t[0] + t[1] * t[1]) + (t[2] * t[2] + t[3] * t[3]); o[64 * j] = (u32x2){cvtpk(t[0], t[1]), cvtpk(t[2], t[3])}; }
;             s = wave_sum(s);
;             if (lane < 16) ss[(size_t)rr * 16 + lane] = lane == 0 ? s : 0.f; } }
.LBB0_333:
	s_waitcnt lgkmcnt(0)
	v_add_f32_e32 v61, v61, v62
	s_lshl_b64 s[0:1], s[44:45], 6
	v_cndmask_b32_e64 v61, 0, v61, s[42:43]
	v_lshl_add_u64 v[62:63], v[54:55], 0, s[0:1]
	global_store_dword v[62:63], v61, off sc1
	s_or_b64 exec, exec, s[76:77]
	s_andn2_b64 vcc, exec, s[74:75]
	s_cbranch_vccnz .LBB0_331
.LBB0_334:
	s_waitcnt vmcnt(15)
	v_mul_f32_e32 v61, v47, v47
	s_waitcnt lgkmcnt(0)
	v_mul_f32_e32 v62, v49, v49
	v_fmac_f32_e32 v61, v46, v46
	v_fmac_f32_e32 v62, v48, v48
	v_add_f32_e32 v61, v61, v62
	s_waitcnt vmcnt(14)
	v_mul_f32_e32 v62, v43, v43
	v_mul_f32_e32 v63, v45, v45
	v_fmac_f32_e32 v62, v42, v42
	v_fmac_f32_e32 v63, v44, v44
	v_add_f32_e32 v62, v62, v63
	v_add_f32_e32 v61, v61, v62
	s_waitcnt vmcnt(13)
	v_mul_f32_e32 v62, v39, v39
	v_mul_f32_e32 v63, v41, v41
	v_fmac_f32_e32 v62, v38, v38
	v_fmac_f32_e32 v63, v40, v40
	v_add_f32_e32 v62, v62, v63
	v_add_f32_e32 v61, v61, v62
	s_waitcnt vmcnt(12)
	v_mul_f32_e32 v62, v35, v35
	v_mul_f32_e32 v63, v37, v37
	v_fmac_f32_e32 v62, v34, v34
	v_fmac_f32_e32 v63, v36, v36
	v_add_f32_e32 v62, v62, v63
	v_add_f32_e32 v61, v61, v62
	ds_bpermute_b32 v62, v0, v61
	s_ashr_i32 s49, s48, 31
	s_lshl_b64 s[0:1], s[48:49], 11
	v_cvt_pk_bf16_f32 v46, v46, v47
	v_cvt_pk_bf16_f32 v47, v48, v49
	s_waitcnt lgkmcnt(0)
	v_add_f32_e32 v61, v61, v62
	ds_bpermute_b32 v62, v56, v61
	v_cvt_pk_bf16_f32 v42, v42, v43
	v_cvt_pk_bf16_f32 v43, v44, v45
	v_cvt_pk_bf16_f32 v34, v34, v35
	v_cvt_pk_bf16_f32 v35, v36, v37
	s_waitcnt lgkmcnt(0)
	v_add_f32_e32 v61, v61, v62
	ds_bpermute_b32 v64, v57, v61
	v_lshl_add_u64 v[62:63], v[52:53], 0, s[0:1]
	global_store_dwordx2 v[62:63], v[46:47], off sc1
	global_store_dwordx2 v[62:63], v[42:43], off offset:512 sc1
	v_cvt_pk_bf16_f32 v42, v38, v39
	s_waitcnt lgkmcnt(0)
	v_add_f32_e32 v61, v61, v64
	ds_bpermute_b32 v64, v58, v61
	v_cvt_pk_bf16_f32 v43, v40, v41
	global_store_dwordx2 v[62:63], v[42:43], off offset:1024 sc1
	global_store_dwordx2 v[62:63], v[34:35], off offset:1536 sc1
	s_waitcnt lgkmcnt(0)
	v_add_f32_e32 v46, v61, v64
	ds_bpermute_b32 v47, v59, v46
	s_waitcnt lgkmcnt(0)
	v_add_f32_e32 v38, v46, v47
	ds_bpermute_b32 v39, v60, v38
	s_and_saveexec_b64 s[44:45], s[40:41]
	s_cbranch_execz .LBB0_336
	s_waitcnt lgkmcnt(0)
	v_add_f32_e32 v34, v38, v39
	s_lshl_b64 s[0:1], s[48:49], 6
	v_cndmask_b32_e64 v36, 0, v34, s[42:43]
	v_lshl_add_u64 v[34:35], v[54:55], 0, s[0:1]
	global_store_dword v[34:35], v36, off sc1

; __device__ __forceinline__ unsigned cvtpk(float lo, float hi) { f32x2_t v = {lo, hi}; bf16x2_t b = __builtin_convertvector(v, bf16x2_t); return __builtin_bit_cast(unsigned, b); }
; __device__ __forceinline__ void prologue_phase(LAS unsigned char* lds, const Args& a, int vcu, int G) {
;     ...
;     const float* x = a.in[0]; bf16_t* xb = (bf16_t*)(a.ws + WS_XB); float* ss = (float*)(a.ws + WS_SS);
;     for (int row = gw; row < M; row += 4 * NGW) {
;         f32x4 v[4][4];
; #pragma unroll
;         for (int q = 0; q < 4; ++q) { const int rr = row + q * NGW < M ? row + q * NGW : row; const f32x4* xr = (const f32x4*)(x + (size_t)rr * DM) + lane;
; #pragma unroll
;             for (int j = 0; j < 4; ++j) v[q][j] = __builtin_nontemporal_load(xr + 64 * j); }
; #pragma unroll
;         for (int q = 0; q < 4; ++q) { const int rr = row + q * NGW; if (rr < M) { u32x2* o = (u32x2*)(xb + (size_t)rr * DM) + lane; float s = 0.f;
; #pragma unroll
;             for (int j = 0; j < 4; ++j) { const f32x4 t = v[q][j]; s += (t[0] * t[0] + t[1] * t[1]) + (t[2] * t[2] + t[3] * t[3]); o[64 * j] = (u32x2){cvtpk(t[0], t[1]), cvtpk(t[2], t[3])}; }
;             s = wave_sum(s);
;             if (lane < 16) ss[(size_t)rr * 16 + lane] = lane == 0 ? s : 0.f; } }
.LBB0_337:
	s_waitcnt vmcnt(11)
	v_mul_f32_e32 v34, v31, v31
	v_mul_f32_e32 v35, v33, v33
	v_fmac_f32_e32 v34, v30, v30
	v_fmac_f32_e32 v35, v32, v32
	v_add_f32_e32 v34, v34, v35
	s_waitcnt vmcnt(10)
	v_mul_f32_e32 v35, v27, v27
	v_mul_f32_e32 v36, v29, v29
	v_fmac_f32_e32 v35, v26, v26
	v_fmac_f32_e32 v36, v28, v28
	v_add_f32_e32 v35, v35, v36
	v_add_f32_e32 v34, v34, v35
	s_waitcnt vmcnt(9)
	v_mul_f32_e32 v35, v23, v23
	v_mul_f32_e32 v36, v25, v25
	v_fmac_f32_e32 v35, v22, v22
	v_fmac_f32_e32 v36, v24, v24
	v_add_f32_e32 v35, v35, v36
	v_add_f32_e32 v34, v34, v35
	s_waitcnt vmcnt(8)
	v_mul_f32_e32 v35, v19, v19
	v_mul_f32_e32 v36, v21, v21
	v_fmac_f32_e32 v35, v18, v18
	v_fmac_f32_e32 v36, v20, v20
	v_add_f32_e32 v35, v35, v36
	v_add_f32_e32 v34, v34, v35
	ds_bpermute_b32 v35, v0, v34
	s_ashr_i32 s53, s52, 31
	s_lshl_b64 s[0:1], s[52:53], 11
	v_cvt_pk_bf16_f32 v30, v30, v31
	v_cvt_pk_bf16_f32 v31, v32, v33
	s_waitcnt lgkmcnt(0)
	v_add_f32_e32 v34, v34, v35
	ds_bpermute_b32 v35, v56, v34
	v_cvt_pk_bf16_f32 v26, v26, v27
	v_cvt_pk_bf16_f32 v27, v28, v29
	v_cvt_pk_bf16_f32 v18, v18, v19
	v_cvt_pk_bf16_f32 v19, v20, v21
	s_waitcnt lgkmcnt(0)
	v_add_f32_e32 v36, v34, v35
	ds_bpermute_b32 v37, v57, v36
	v_lshl_add_u64 v[34:35], v[52:53], 0, s[0:1]
	global_store_dwordx2 v[34:35], v[30:31], off sc1
	global_store_dwordx2 v[34:35], v[26:27], off offset:512 sc1
	v_cvt_pk_bf16_f32 v26, v22, v23
	s_waitcnt lgkmcnt(0)
	v_add_f32_e32 v36, v36, v37
	ds_bpermute_b32 v37, v58, v36
	v_cvt_pk_bf16_f32 v27, v24, v25
	global_store_dwordx2 v[34:35], v[26:27], off offset:1024 sc1
	global_store_dwordx2 v[34:35], v[18:19], off offset:1536 sc1
	s_waitcnt lgkmcnt(0)
	v_add_f32_e32 v30, v36, v37
	ds_bpermute_b32 v31, v59, v30
	s_waitcnt lgkmcnt(0)
	v_add_f32_e32 v22, v30, v31
	ds_bpermute_b32 v23, v60, v22
	s_and_saveexec_b64 s[44:45], s[40:41]
	s_cbranch_execz .LBB0_339
	s_waitcnt lgkmcnt(0)
	v_add_f32_e32 v18, v22, v23
	s_lshl_b64 s[0:1], s[52:53], 6
	v_cndmask_b32_e64 v20, 0, v18, s[42:43]
	v_lshl_add_u64 v[18:19], v[54:55], 0, s[0:1]
	global_store_dword v[18:19], v20, off sc1

; __device__ __forceinline__ unsigned cvtpk(float lo, float hi) { f32x2_t v = {lo, hi}; bf16x2_t b = __builtin_convertvector(v, bf16x2_t); return __builtin_bit_cast(unsigned, b); }
; __device__ __forceinline__ void prologue_phase(LAS unsigned char* lds, const Args& a, int vcu, int G) {
;     ...
;     const float* x = a.in[0]; bf16_t* xb = (bf16_t*)(a.ws + WS_XB); float* ss = (float*)(a.ws + WS_SS);
;     for (int row = gw; row < M; row += 4 * NGW) {
;         f32x4 v[4][4];
; #pragma unroll
;         for (int q = 0; q < 4; ++q) { const int rr = row + q * NGW < M ? row + q * NGW : row; const f32x4* xr = (const f32x4*)(x + (size_t)rr * DM) + lane;
; #pragma unroll
;             for (int j = 0; j < 4; ++j) v[q][j] = __builtin_nontemporal_load(xr + 64 * j); }
; #pragma unroll
;         for (int q = 0; q < 4; ++q) { const int rr = row + q * NGW; if (rr < M) { u32x2* o = (u32x2*)(xb + (size_t)rr * DM) + lane; float s = 0.f;
; #pragma unroll
;             for (int j = 0; j < 4; ++j) { const f32x4 t = v[q][j]; s += (t[0] * t[0] + t[1] * t[1]) + (t[2] * t[2] + t[3] * t[3]); o[64 * j] = (u32x2){cvtpk(t[0], t[1]), cvtpk(t[2], t[3])}; }
;             s = wave_sum(s);
;             if (lane < 16) ss[(size_t)rr * 16 + lane] = lane == 0 ? s : 0.f; } }
.LBB0_340:
	s_waitcnt vmcnt(7)
	v_mul_f32_e32 v18, v15, v15
	v_mul_f32_e32 v19, v17, v17
	v_fmac_f32_e32 v18, v14, v14
	v_fmac_f32_e32 v19, v16, v16
	v_add_f32_e32 v18, v18, v19
	s_waitcnt vmcnt(6)
	v_mul_f32_e32 v19, v11, v11
	v_mul_f32_e32 v20, v13, v13
	v_fmac_f32_e32 v19, v10, v10
	v_fmac_f32_e32 v20, v12, v12
	v_add_f32_e32 v19, v19, v20
	v_add_f32_e32 v18, v18, v19
	s_waitcnt vmcnt(5)
	v_mul_f32_e32 v19, v7, v7
	v_mul_f32_e32 v20, v9, v9
	v_fmac_f32_e32 v19, v6, v6
	v_fmac_f32_e32 v20, v8, v8
	v_add_f32_e32 v19, v19, v20
	v_add_f32_e32 v18, v18, v19
	s_waitcnt vmcnt(4)
	v_mul_f32_e32 v19, v3, v3
	v_mul_f32_e32 v20, v5, v5
	v_fmac_f32_e32 v19, v2, v2
	v_fmac_f32_e32 v20, v4, v4
	v_add_f32_e32 v19, v19, v20
	v_add_f32_e32 v18, v18, v19
	ds_bpermute_b32 v19, v0, v18
	s_ashr_i32 s51, s50, 31
	s_lshl_b64 s[0:1], s[50:51], 11
	v_cvt_pk_bf16_f32 v14, v14, v15
	v_cvt_pk_bf16_f32 v15, v16, v17
	s_waitcnt lgkmcnt(0)
	v_add_f32_e32 v18, v18, v19
	ds_bpermute_b32 v19, v56, v18
	v_cvt_pk_bf16_f32 v10, v10, v11
	v_cvt_pk_bf16_f32 v11, v12, v13
	v_cvt_pk_bf16_f32 v2, v2, v3
	v_cvt_pk_bf16_f32 v3, v4, v5
	s_waitcnt lgkmcnt(0)
	v_add_f32_e32 v20, v18, v19
	ds_bpermute_b32 v21, v57, v20
	v_lshl_add_u64 v[18:19], v[52:53], 0, s[0:1]
	global_store_dwordx2 v[18:19], v[14:15], off sc1
	global_store_dwordx2 v[18:19], v[10:11], off offset:512 sc1
	v_cvt_pk_bf16_f32 v10, v6, v7
	s_waitcnt lgkmcnt(0)
	v_add_f32_e32 v20, v20, v21
	ds_bpermute_b32 v21, v58, v20
	v_cvt_pk_bf16_f32 v11, v8, v9
	global_store_dwordx2 v[18:19], v[10:11], off offset:1024 sc1
	global_store_dwordx2 v[18:19], v[2:3], off offset:1536 sc1
	s_waitcnt lgkmcnt(0)
	v_add_f32_e32 v14, v20, v21
	ds_bpermute_b32 v15, v59, v14
	s_waitcnt lgkmcnt(0)
	v_add_f32_e32 v6, v14, v15
	ds_bpermute_b32 v7, v60, v6
	s_and_saveexec_b64 s[44:45], s[40:41]
	s_cbranch_execz .LBB0_327
	s_waitcnt lgkmcnt(0)
	v_add_f32_e32 v2, v6, v7
	s_lshl_b64 s[0:1], s[50:51], 6
	v_cndmask_b32_e64 v4, 0, v2, s[42:43]
	v_lshl_add_u64 v[2:3], v[54:55], 0, s[0:1]
	global_store_dword v[2:3], v4, off sc1
	s_branch .LBB0_327

; __device__ __forceinline__ unsigned xb_ld(unsigned* p)              { return __hip_atomic_load(p, __ATOMIC_RELAXED, __HIP_MEMORY_SCOPE_AGENT); }
; __device__ __forceinline__ unsigned xb_add(unsigned* p, unsigned v) { return __hip_atomic_fetch_add(p, v, __ATOMIC_RELAXED, __HIP_MEMORY_SCOPE_AGENT); }
; #define XB_SPIN(cond, bar) do { unsigned _sp = 0; while (cond) { __builtin_amdgcn_s_sleep(1); \
;     if ((++_sp & 255u) == 0u) { if (xb_ld(&(bar)[XB_TMO])) break; if (_sp > XB_SPIN_CAP) { atomicAdd(&(bar)[XB_TMO], 1u); break; } } } } while (0)
; __device__ __forceinline__ void xcd_barrier(const XcdBarrier& b) {
;     asm volatile("s_waitcnt vmcnt(0)" ::: "memory");
;     __syncthreads();
;     if (threadIdx.x == 0) {
;         unsigned* bar = b.bar;
;         __builtin_amdgcn_s_waitcnt(0);
;         unsigned nloc = b.st[0], nx = b.st[1];
;         if (nloc == 0u) { xcd_barrier_complete(bar, b.x, nloc, nx); b.st[0] = nloc; b.st[1] = nx; }
;         const unsigned old = xb_add(&bar[XB_XSUB(b.x)], 1u);
;         const unsigned gen = old / nloc;
;         if (old + 1u == (gen + 1u) * nloc) {
;             __builtin_amdgcn_fence(__ATOMIC_RELEASE, "agent");
;             asm volatile("s_waitcnt vmcnt(0)" ::: "memory");
;             const unsigned og = xb_add(&bar[XB_TOP], 1u);
;             const unsigned tg = og / nx;
;             if (og + 1u == (tg + 1u) * nx) xb_add(&bar[XB_TOPGEN], 1u);
;             else XB_SPIN(xb_ld(&bar[XB_TOPGEN]) == tg, bar);
;             __builtin_amdgcn_fence(__ATOMIC_ACQUIRE, "agent");
;             xb_add(&bar[XB_XGEN(b.x)], 1u);
.LBB0_388:
	s_andn2_saveexec_b64 s[0:1], s[42:43]
	s_cbranch_execz .LBB0_10
	s_mov_b64 s[42:43], exec
	s_lshl_b32 s0, 1, s76
	s_and_b32 s0, s0, 0xe2c8
	s_cbranch_scc0 .Lgb_global
	v_readlane_b32 s0, v254, 38
	s_nop 1
	v_mov_b32_e32 v18, s0
	ds_read_b32 v19, v18 offset:8
	s_waitcnt lgkmcnt(0)
	v_readfirstlane_b32 s0, v19
	s_cmp_eq_u32 s0, 1
	s_cbranch_scc1 .LBB0_405
	s_cmp_eq_u32 s0, 2
	s_cbranch_scc1 .Lgb_global
	v_readlane_b32 s0, v254, 62
	v_readlane_b32 s1, v254, 63
	s_nop 1
	s_load_dwordx2 s[44:45], s[0:1], 0xa0
	s_waitcnt lgkmcnt(0)
	s_add_u32 s44, s44, 0xda04000
	s_addc_u32 s45, s45, 0
	v_mov_b32_e32 v20, 0
	global_load_dword v21, v20, s[44:45] sc1
	global_load_dword v22, v20, s[44:45] offset:256 sc1
	global_load_dword v23, v20, s[44:45] offset:512 sc1
	global_load_dword v24, v20, s[44:45] offset:768 sc1
	global_load_dword v25, v20, s[44:45] offset:1024 sc1
	global_load_dword v26, v20, s[44:45] offset:1280 sc1
	global_load_dword v27, v20, s[44:45] offset:1536 sc1
	global_load_dword v28, v20, s[44:45] offset:1792 sc1
	s_waitcnt vmcnt(0)
	v_add_u32_e32 v29, -1, v21
	v_and_b32_e32 v29, v29, v21
	v_mov_b32_e32 v30, v21
	v_add_u32_e32 v31, -1, v22
	v_and_b32_e32 v31, v31, v22
	v_or_b32_e32 v29, v29, v31
	v_min_u32_e32 v30, v30, v22
	v_add_u32_e32 v31, -1, v23
	v_and_b32_e32 v31, v31, v23
	v_or_b32_e32 v29, v29, v31
	v_min_u32_e32 v30, v30, v23
	v_add_u32_e32 v31, -1, v24
	v_and_b32_e32 v31, v31, v24
	v_or_b32_e32 v29, v29, v31
	v_min_u32_e32 v30, v30, v24
	v_add_u32_e32 v31, -1, v25
	v_and_b32_e32 v31, v31, v25
	v_or_b32_e32 v29, v29, v31
	v_min_u32_e32 v30, v30, v25
	v_add_u32_e32 v31, -1, v26
	v_and_b32_e32 v31, v31, v26
	v_or_b32_e32 v29, v29, v31
	v_min_u32_e32 v30, v30, v26
	v_add_u32_e32 v31, -1, v27
	v_and_b32_e32 v31, v31, v27
	v_or_b32_e32 v29, v29, v31
	v_min_u32_e32 v30, v30, v27
	v_add_u32_e32 v31, -1, v28
	v_and_b32_e32 v31, v31, v28
	v_or_b32_e32 v29, v29, v31
	v_min_u32_e32 v30, v30, v28
	v_cmp_eq_u32_e32 vcc, 0, v29
	v_cmp_ne_u32_e64 s[0:1], 0, v30
	s_nop 1
	s_and_b64 s[0:1], s[0:1], vcc
	s_and_b64 s[0:1], s[0:1], exec
	s_cselect_b32 s0, 1, 2
	v_mov_b32_e32 v19, s0
	ds_write_b32 v18, v19 offset:8
	s_waitcnt lgkmcnt(0)
	s_cmp_eq_u32 s0, 1
	s_cbranch_scc1 .LBB0_405
.Lgb_global:
	s_lshl_b32 s0, 1, s76
	s_and_b32 s0, s0, 0x506
	s_cbranch_scc1 .Lgb_nowb
	buffer_wbl2 sc1
.Lgb_nowb:
	s_waitcnt lgkmcnt(0)
	s_waitcnt vmcnt(0)
	v_mbcnt_lo_u32_b32 v0, s42, 0
	v_mbcnt_hi_u32_b32 v0, s43, v0
	v_cmp_eq_u32_e32 vcc, 0, v0
	s_and_saveexec_b64 s[44:45], vcc
	s_cbranch_execz .LBB0_391
	s_bcnt1_i32_b64 s0, s[42:43]
	v_mov_b32_e32 v3, s0
	v_readlane_b32 s0, v254, 8
	v_readlane_b32 s1, v254, 9
	s_nop 4
	global_atomic_add v3, v1, v3, s[0:1] sc0
